# P1c: SGPR-base LDS-DMA addressing, tile-start vmcnt(0) hoisted out of tile loop, B0 fragment reads issued one half-phase earlier into spare VGPRs
# speedup vs baseline: 1.0042x; 1.0042x over previous
; #define G_STAGE(bufoff, gbase, voff) do { _Pragma("unroll") for (int _i = 0; _i < 2; ++_i) \
;         __builtin_amdgcn_global_load_lds((const unsigned*)((const char*)(gbase) + (voff)[_i]), (LAS unsigned*)(lds + (bufoff) + ldsw + _i * 8192), 16, 0, 0); } while (0)
; #define G_WAIT_V(n) asm volatile("s_waitcnt vmcnt(" #n ")" ::: "memory")
; #define G_BAR __builtin_amdgcn_s_barrier()
; template <int MODE  , class Epi, class Sched>
; __device__ __forceinline__ void gemm_phase(LAS unsigned char* lds, const GemmDesc g, const Sched& S, const Epi& E) {
;     ...
;     for (int i = 0; i < 2; ++i) { int R, C; stage_rc(tid * 16 + i * 8192, R, C); const int Rb = (R & ~31) + perm32(R & 31);
;         voffA[i] = (unsigned)(R * g.lda + C) * 2u; voffB[i] = (unsigned)(Rb * g.ldb + C) * 2u; }
;     const size_t kstep = (size_t)(BK * 2);
;     const size_t hstepA = (size_t)HALF * g.lda * 2, hstepB = (size_t)HALF * g.ldb * 2;
;     const size_t khb = (size_t)nt * kstep;
;     const unsigned ldsw = (unsigned)wid * 1024u;
;     const int aoff = lds_byte(wr * 64 + fr, fq * 8), boff = lds_byte(wc * 32 + fr, fq * 8);
;     ...
;     const char* cA = (const char*)(cur.type ? g.A2 : g.A) + (size_t)cur.pm * 2 * hstepA + (size_t)cur.kh * khb;
;     const char* cB = (const char*)(cur.type ? g.Bt2 : g.Bt) + (size_t)cur.pn * 2 * hstepB + (size_t)cur.kh * khb;
;     G_STAGE(G_SB(0, 0), cB, voffB); G_STAGE(G_SA(0, 0), cA, voffA); G_STAGE(G_SB(0, 1), cB + hstepB, voffB); G_STAGE(G_SA(0, 1), cA + hstepA, voffA);
;     if (wr == 1) G_BAR;
;     G_WAIT_V(4); G_BAR;
;     G_STAGE(G_SB(1, 0), cB + kstep, voffB); G_STAGE(G_SA(1, 0), cA + kstep, voffA); G_STAGE(G_SB(1, 1), cB + hstepB + kstep, voffB);
;     G_WAIT_V(6); G_BAR;
.LBB0_518:
	s_add_u32 s4, s26, 0x39615000
	s_addc_u32 s5, s27, 0
	s_lshl_b32 s2, s2, 5
	s_mov_b64 s[16:17], 0x80
	s_and_b32 s11, s2, 0x60
	s_add_i32 m0, s55, 0x18000
	v_lshl_add_u64 v[8:9], v[8:9], 0, s[16:17]
	s_lshl_b32 s10, s0, 13
	s_lshl_b32 s18, s11, 7
	s_waitcnt vmcnt(4)
	s_barrier
	global_load_lds_dwordx4 v[8:9], off
	v_lshl_add_u64 v[6:7], v[6:7], 0, s[16:17]
	s_add_i32 m0, s55, 0x1a000
	s_add_i32 s60, s55, 0x8000
	s_add_i32 s61, s55, 0xa000
	global_load_lds_dwordx4 v[6:7], off
	v_lshl_add_u64 v[4:5], v[4:5], 0, s[16:17]
	s_mov_b32 m0, s60
	s_add_u32 s2, s40, 0x44080
	global_load_lds_dwordx4 v[4:5], off
	v_lshl_add_u64 v[2:3], v[2:3], 0, s[16:17]
	s_mov_b32 m0, s61
	s_addc_u32 s3, s41, 0
	global_load_lds_dwordx4 v[2:3], off
	s_add_i32 m0, s55, 0x1c000
	v_lshl_add_u64 v[2:3], s[2:3], 0, v[148:149]
	global_load_lds_dwordx4 v[2:3], off
	v_lshl_add_u64 v[2:3], s[2:3], 0, v[152:153]
	s_add_i32 m0, s55, 0x1e000
	s_mov_b64 s[2:3], 0x44080
	global_load_lds_dwordx4 v[2:3], off
	v_lshrrev_b32_e32 v3, 1, v10
	v_and_b32_e32 v3, 24, v3
	v_and_b32_e32 v2, 15, v10
	v_lshlrev_b32_e32 v4, 1, v3
	v_lshl_or_b32 v1, s0, 6, v2
	v_lshl_or_b32 v2, v2, 6, v4
	v_lshlrev_b32_e32 v4, 2, v10
	v_or_b32_e32 v192, s11, v3
	v_and_b32_e32 v4, 32, v4
	v_lshlrev_b32_e32 v154, 2, v192
	v_bitop3_b32 v5, v2, s10, v4 bitop3:0xde
	v_bitop3_b32 v191, v2, s18, v4 bitop3:0xde
	v_lshl_add_u64 v[2:3], s[26:27], 0, v[154:155]
	s_mov_b64 s[10:11], 0x3960f000
	v_lshl_add_u64 v[156:157], v[2:3], 0, s[10:11]
	v_lshrrev_b32_e32 v3, 1, v11
	v_mul_lo_u32 v2, v13, s1
	s_movk_i32 s0, 0x4400
	v_mad_u64_u32 v[2:3], s[10:11], v3, s0, v[2:3]
	v_or_b32_e32 v2, v2, v12
	v_add_lshl_u32 v154, v2, v14, 1
	v_lshrrev_b32_e32 v3, 1, v15
	v_mul_lo_u32 v2, v16, s1
	v_mad_u64_u32 v[2:3], s[0:1], v3, s0, v[2:3]
	s_waitcnt vmcnt(6)
	v_or_b32_e32 v2, v2, v17
	s_add_i32 s66, 0, 0x10000
	s_add_i32 s68, 0, 0x14000
	v_lshl_add_u64 v[158:159], v[154:155], 0, s[2:3]
	v_add_lshl_u32 v154, v2, v18, 1
	v_add_u32_e32 v193, s66, v191
	v_add_u32_e32 v195, s68, v191
	s_add_i32 s66, s66, s54
	s_add_i32 s68, s68, s54
	v_lshl_add_u64 v[160:161], v[154:155], 0, s[2:3]
	s_movk_i32 s62, 0x199
	v_add_u32_e32 v194, 0, v5
	s_mov_b32 s63, 0xc2200000
	s_add_i32 s64, s55, 0xc000
	s_add_i32 s65, s55, 0xe000
	s_add_i32 s67, s66, 0x2000
	s_add_i32 s69, s68, 0x2000
	v_mov_b32_e32 v196, 0x42200000
	s_waitcnt vmcnt(0)
	s_barrier
	ds_read_b128 v[232:235], v193
	ds_read_b128 v[236:239], v193 offset:1024
	ds_read_b128 v[240:243], v193 offset:2048
	ds_read_b128 v[244:247], v193 offset:3072
	s_branch .LBB0_520

; #define G_STAGE(bufoff, gbase, voff) do { _Pragma("unroll") for (int _i = 0; _i < 2; ++_i) \
;         __builtin_amdgcn_global_load_lds((const unsigned*)((const char*)(gbase) + (voff)[_i]), (LAS unsigned*)(lds + (bufoff) + ldsw + _i * 8192), 16, 0, 0); } while (0)
; #define G_WAIT_L(n) asm volatile("s_waitcnt lgkmcnt(" #n ")" ::: "memory")
; #define G_BAR __builtin_amdgcn_s_barrier()
; #define G_SCHED __builtin_amdgcn_sched_barrier(0)
; template <int MODE  , class Epi, class Sched>
; __device__ __forceinline__ void gemm_phase(LAS unsigned char* lds, const GemmDesc g, const Sched& S, const Epi& E) {
;     ...
;         for (int t = 0; t < nt; t += 2) {
;             const bool last = (t == nt - 2);
;             const char* a1 = cA + (size_t)(t + 1) * kstep;
;             const char* a2 = last ? nA : cA + (size_t)(t + 2) * kstep; const char* b2 = last ? nB : cB + (size_t)(t + 2) * kstep;
;             const char* a3 = a2 + kstep; const char* b3 = b2 + kstep;
;             G_LDB(B0, 0, 0); G_SCHED; G_LDA(At, 0, 0); G_STAGE(G_SA(1, 1), a1 + hstepA, voffA);
;             G_WAIT_L(8); G_BAR; G_WAIT_L(0); G_MMA(0, 0, At, B0); G_BAR; G_SCHED;
;             G_LDB(B1, 0, 1); G_STAGE(G_SB(0, 0), b2, voffB);
;             G_BAR; G_WAIT_L(0); G_MMA(0, 1, At, B1); G_BAR;
;             G_LDA(At, 0, 1); G_STAGE(G_SA(0, 0), a2, voffA);
;     ...
; #pragma unroll
;             for (int a = 0; a < 2; ++a)
; #pragma unroll
;                 for (int b = 0; b < 2; ++b)
; #pragma unroll
;                     for (int m = 0; m < 4; ++m)
; #pragma unroll
;                         for (int n = 0; n < 2; ++n) acc[a][b][m][n] = (f32x4){0.f, 0.f, 0.f, 0.f};
.LBB0_526:
	s_add_u32 s72, s40, 0x100
	v_mov_b32_e32 v10, 0
	s_addc_u32 s76, s41, 0
	s_mov_b32 s77, -2
	v_mov_b32_e32 v11, v10
	v_mov_b32_e32 v12, v10
	v_mov_b32_e32 v13, v10
	v_mov_b32_e32 v14, v10
	v_mov_b32_e32 v15, v10
	v_mov_b32_e32 v16, v10
	v_mov_b32_e32 v17, v10
	v_mov_b32_e32 v26, v10
	v_mov_b32_e32 v27, v10
	v_mov_b32_e32 v28, v10
	v_mov_b32_e32 v29, v10
	v_mov_b32_e32 v30, v10
	v_mov_b32_e32 v31, v10
	v_mov_b32_e32 v32, v10
	v_mov_b32_e32 v33, v10
	v_mov_b32_e32 v58, v10
	v_mov_b32_e32 v59, v10
	v_mov_b32_e32 v60, v10
	v_mov_b32_e32 v61, v10
	v_mov_b32_e32 v62, v10
	v_mov_b32_e32 v63, v10
	v_mov_b32_e32 v64, v10
	v_mov_b32_e32 v65, v10
	v_mov_b32_e32 v74, v10
	v_mov_b32_e32 v75, v10
	v_mov_b32_e32 v76, v10
	v_mov_b32_e32 v77, v10
	v_mov_b32_e32 v78, v10
	v_mov_b32_e32 v79, v10
	v_mov_b32_e32 v80, v10
	v_mov_b32_e32 v81, v10
	v_mov_b32_e32 v2, v10
	v_mov_b32_e32 v3, v10
	v_mov_b32_e32 v4, v10
	v_mov_b32_e32 v5, v10
	v_mov_b32_e32 v6, v10
	v_mov_b32_e32 v7, v10
	v_mov_b32_e32 v8, v10
	v_mov_b32_e32 v9, v10
	v_mov_b32_e32 v18, v10
	v_mov_b32_e32 v19, v10
	v_mov_b32_e32 v20, v10
	v_mov_b32_e32 v21, v10
	v_mov_b32_e32 v22, v10
	v_mov_b32_e32 v23, v10
	v_mov_b32_e32 v24, v10
	v_mov_b32_e32 v25, v10
	v_mov_b32_e32 v50, v10
	v_mov_b32_e32 v51, v10
	v_mov_b32_e32 v52, v10
	v_mov_b32_e32 v53, v10
	v_mov_b32_e32 v54, v10
	v_mov_b32_e32 v55, v10
	v_mov_b32_e32 v56, v10
	v_mov_b32_e32 v57, v10
	v_mov_b32_e32 v66, v10
	v_mov_b32_e32 v67, v10
	v_mov_b32_e32 v68, v10
	v_mov_b32_e32 v69, v10
	v_mov_b32_e32 v70, v10
	v_mov_b32_e32 v71, v10
	v_mov_b32_e32 v72, v10
	v_mov_b32_e32 v73, v10
	v_mov_b32_e32 v90, v10
	v_mov_b32_e32 v91, v10
	v_mov_b32_e32 v92, v10
	v_mov_b32_e32 v93, v10
	v_mov_b32_e32 v94, v10
	v_mov_b32_e32 v95, v10
	v_mov_b32_e32 v96, v10
	v_mov_b32_e32 v97, v10
	v_mov_b32_e32 v106, v10
	v_mov_b32_e32 v107, v10
	v_mov_b32_e32 v108, v10
	v_mov_b32_e32 v109, v10
	v_mov_b32_e32 v110, v10
	v_mov_b32_e32 v111, v10
	v_mov_b32_e32 v112, v10
	v_mov_b32_e32 v113, v10
	v_mov_b32_e32 v122, v10
	v_mov_b32_e32 v123, v10
	v_mov_b32_e32 v124, v10
	v_mov_b32_e32 v125, v10
	v_mov_b32_e32 v126, v10
	v_mov_b32_e32 v127, v10
	v_mov_b32_e32 v128, v10
	v_mov_b32_e32 v129, v10
	v_mov_b32_e32 v138, v10
	v_mov_b32_e32 v139, v10
	v_mov_b32_e32 v140, v10
	v_mov_b32_e32 v141, v10
	v_mov_b32_e32 v142, v10
	v_mov_b32_e32 v143, v10
	v_mov_b32_e32 v144, v10
	v_mov_b32_e32 v145, v10
	v_mov_b32_e32 v82, v10
	v_mov_b32_e32 v83, v10
	v_mov_b32_e32 v84, v10
	v_mov_b32_e32 v85, v10
	v_mov_b32_e32 v86, v10
	v_mov_b32_e32 v87, v10
	v_mov_b32_e32 v88, v10
	v_mov_b32_e32 v89, v10
	v_mov_b32_e32 v98, v10
	v_mov_b32_e32 v99, v10
	v_mov_b32_e32 v100, v10
	v_mov_b32_e32 v101, v10
	v_mov_b32_e32 v102, v10
	v_mov_b32_e32 v103, v10
	v_mov_b32_e32 v104, v10
	v_mov_b32_e32 v105, v10
	v_mov_b32_e32 v114, v10
	v_mov_b32_e32 v115, v10
	v_mov_b32_e32 v116, v10
	v_mov_b32_e32 v117, v10
	v_mov_b32_e32 v118, v10
	v_mov_b32_e32 v119, v10
	v_mov_b32_e32 v120, v10
	v_mov_b32_e32 v121, v10
	v_mov_b32_e32 v130, v10
	v_mov_b32_e32 v131, v10
	v_mov_b32_e32 v132, v10
	v_mov_b32_e32 v133, v10
	v_mov_b32_e32 v134, v10
	v_mov_b32_e32 v135, v10
	v_mov_b32_e32 v136, v10
	v_mov_b32_e32 v137, v10
.LBB0_527:
	s_add_u32 s40, s34, 0x100
	s_addc_u32 s41, s35, 0
	s_cmp_eq_u32 s77, 12
	s_cselect_b32 s47, s21, s41
	s_cselect_b32 s46, s20, s40
	s_cselect_b32 s45, s3, s76
	s_cselect_b32 s44, s2, s72
	s_mov_b32 m0, s64
	s_add_u32 s98, s34, 0x44080
	s_addc_u32 s99, s35, 0
	ds_read_b128 v[162:165], v194
	ds_read_b128 v[166:169], v194 offset:1024
	ds_read_b128 v[170:173], v194 offset:2048
	ds_read_b128 v[174:177], v194 offset:3072
	ds_read_b128 v[178:181], v194 offset:4096
	ds_read_b128 v[182:185], v194 offset:5120
	ds_read_b128 v[186:189], v194 offset:6144
	ds_read_b128 v[198:201], v194 offset:7168
	global_load_lds_dwordx4 v146, s[98:99]
	s_mov_b32 m0, s65
	s_nop 0
	global_load_lds_dwordx4 v150, s[98:99]
	s_waitcnt lgkmcnt(8)
	s_barrier
	s_waitcnt lgkmcnt(0)
	s_setprio 1
	s_waitcnt lgkmcnt(0)
	v_mfma_i32_16x16x64_i8 v[134:137], v[232:235], v[162:165], v[134:137]
	v_mfma_i32_16x16x64_i8 v[130:133], v[240:243], v[162:165], v[130:133]
	v_mfma_i32_16x16x64_i8 v[118:121], v[232:235], v[170:173], v[118:121]
	v_mfma_i32_16x16x64_i8 v[114:117], v[240:243], v[170:173], v[114:117]
	v_mfma_i32_16x16x64_i8 v[102:105], v[232:235], v[178:181], v[102:105]
	v_mfma_i32_16x16x64_i8 v[98:101], v[240:243], v[178:181], v[98:101]
	v_mfma_i32_16x16x64_i8 v[86:89], v[232:235], v[186:189], v[86:89]
	v_mfma_i32_16x16x64_i8 v[82:85], v[240:243], v[186:189], v[82:85]
	v_mfma_i32_16x16x64_i8 v[134:137], v[236:239], v[166:169], v[134:137]
	v_mfma_i32_16x16x64_i8 v[130:133], v[244:247], v[166:169], v[130:133]
	v_mfma_i32_16x16x64_i8 v[118:121], v[236:239], v[174:177], v[118:121]
	v_mfma_i32_16x16x64_i8 v[114:117], v[244:247], v[174:177], v[114:117]
	v_mfma_i32_16x16x64_i8 v[102:105], v[236:239], v[182:185], v[102:105]
	v_mfma_i32_16x16x64_i8 v[98:101], v[244:247], v[182:185], v[98:101]
	v_mfma_i32_16x16x64_i8 v[86:89], v[236:239], v[198:201], v[86:89]
	v_mfma_i32_16x16x64_i8 v[82:85], v[244:247], v[198:201], v[82:85]
	s_setprio 0
	s_barrier
	s_mov_b32 m0, s66
	ds_read_b128 v[202:205], v195
	ds_read_b128 v[206:209], v195 offset:1024
	ds_read_b128 v[210:213], v195 offset:2048
	ds_read_b128 v[214:217], v195 offset:3072
	global_load_lds_dwordx4 v148, s[44:45]
	s_mov_b32 m0, s67
	s_nop 0
	global_load_lds_dwordx4 v152, s[44:45]
	s_barrier
; #define G_STAGE(bufoff, gbase, voff) do { _Pragma("unroll") for (int _i = 0; _i < 2; ++_i) \
;         __builtin_amdgcn_global_load_lds((const unsigned*)((const char*)(gbase) + (voff)[_i]), (LAS unsigned*)(lds + (bufoff) + ldsw + _i * 8192), 16, 0, 0); } while (0)
; #define G_WAIT_V(n) asm volatile("s_waitcnt vmcnt(" #n ")" ::: "memory")
; #define G_WAIT_L(n) asm volatile("s_waitcnt lgkmcnt(" #n ")" ::: "memory")
; #define G_BAR __builtin_amdgcn_s_barrier()
; #define G_SCHED __builtin_amdgcn_sched_barrier(0)
; template <int MODE  , class Epi, class Sched>
; __device__ __forceinline__ void gemm_phase(LAS unsigned char* lds, const GemmDesc g, const Sched& S, const Epi& E) {
;     ...
;             G_BAR; G_WAIT_L(0); G_MMA(0, 1, At, B1); G_BAR;
;             G_LDA(At, 0, 1); G_STAGE(G_SA(0, 0), a2, voffA);
;             G_BAR; G_WAIT_L(0); G_MMA(1, 0, At, B0); G_BAR; G_SCHED;
;             G_STAGE(G_SB(0, 1), b2 + hstepB, voffB);
;             G_WAIT_V(6); G_BAR; G_MMA(1, 1, At, B1); G_BAR;
;             G_LDB(B0, 1, 0); G_SCHED; G_LDA(At, 1, 0); G_STAGE(G_SA(0, 1), a2 + hstepA, voffA);
;             G_WAIT_L(8); G_BAR; G_WAIT_L(0); G_MMA(0, 0, At, B0); G_BAR; G_SCHED;
;             G_LDB(B1, 1, 1); G_STAGE(G_SB(1, 0), b3, voffB);
;             G_BAR; G_WAIT_L(0); G_MMA(0, 1, At, B1); G_BAR;
;             G_LDA(At, 1, 1); G_STAGE(G_SA(1, 0), a3, voffA);
	s_waitcnt lgkmcnt(0)
	s_setprio 1
	s_waitcnt lgkmcnt(0)
	v_mfma_i32_16x16x64_i8 v[142:145], v[202:205], v[162:165], v[142:145]
	v_mfma_i32_16x16x64_i8 v[138:141], v[210:213], v[162:165], v[138:141]
	v_mfma_i32_16x16x64_i8 v[126:129], v[202:205], v[170:173], v[126:129]
	v_mfma_i32_16x16x64_i8 v[122:125], v[210:213], v[170:173], v[122:125]
	v_mfma_i32_16x16x64_i8 v[110:113], v[202:205], v[178:181], v[110:113]
	v_mfma_i32_16x16x64_i8 v[106:109], v[210:213], v[178:181], v[106:109]
	v_mfma_i32_16x16x64_i8 v[94:97], v[202:205], v[186:189], v[94:97]
	v_mfma_i32_16x16x64_i8 v[90:93], v[210:213], v[186:189], v[90:93]
	v_mfma_i32_16x16x64_i8 v[142:145], v[206:209], v[166:169], v[142:145]
	v_mfma_i32_16x16x64_i8 v[138:141], v[214:217], v[166:169], v[138:141]
	v_mfma_i32_16x16x64_i8 v[126:129], v[206:209], v[174:177], v[126:129]
	v_mfma_i32_16x16x64_i8 v[122:125], v[214:217], v[174:177], v[122:125]
	v_mfma_i32_16x16x64_i8 v[110:113], v[206:209], v[182:185], v[110:113]
	v_mfma_i32_16x16x64_i8 v[106:109], v[214:217], v[182:185], v[106:109]
	v_mfma_i32_16x16x64_i8 v[94:97], v[206:209], v[198:201], v[94:97]
	v_mfma_i32_16x16x64_i8 v[90:93], v[214:217], v[198:201], v[90:93]
	s_setprio 0
	s_mov_b32 m0, s55
	s_barrier
	ds_read_b128 v[162:165], v194 offset:16384
	ds_read_b128 v[166:169], v194 offset:17408
	ds_read_b128 v[170:173], v194 offset:18432
	ds_read_b128 v[174:177], v194 offset:19456
	ds_read_b128 v[178:181], v194 offset:20480
	ds_read_b128 v[182:185], v194 offset:21504
	ds_read_b128 v[186:189], v194 offset:22528
	ds_read_b128 v[198:201], v194 offset:23552
	global_load_lds_dwordx4 v146, s[46:47]
	s_mov_b32 m0, s56
	s_nop 0
	global_load_lds_dwordx4 v150, s[46:47]
	s_barrier
	s_waitcnt lgkmcnt(0)
	s_setprio 1
	s_waitcnt lgkmcnt(0)
	v_mfma_i32_16x16x64_i8 v[70:73], v[232:235], v[162:165], v[70:73]
	v_mfma_i32_16x16x64_i8 v[66:69], v[240:243], v[162:165], v[66:69]
	v_mfma_i32_16x16x64_i8 v[54:57], v[232:235], v[170:173], v[54:57]
	v_mfma_i32_16x16x64_i8 v[50:53], v[240:243], v[170:173], v[50:53]
	v_mfma_i32_16x16x64_i8 v[22:25], v[232:235], v[178:181], v[22:25]
	v_mfma_i32_16x16x64_i8 v[18:21], v[240:243], v[178:181], v[18:21]
	v_mfma_i32_16x16x64_i8 v[6:9], v[232:235], v[186:189], v[6:9]
	v_mfma_i32_16x16x64_i8 v[2:5], v[240:243], v[186:189], v[2:5]
	v_mfma_i32_16x16x64_i8 v[70:73], v[236:239], v[166:169], v[70:73]
	v_mfma_i32_16x16x64_i8 v[66:69], v[244:247], v[166:169], v[66:69]
	v_mfma_i32_16x16x64_i8 v[54:57], v[236:239], v[174:177], v[54:57]
	v_mfma_i32_16x16x64_i8 v[50:53], v[244:247], v[174:177], v[50:53]
	v_mfma_i32_16x16x64_i8 v[22:25], v[236:239], v[182:185], v[22:25]
	v_mfma_i32_16x16x64_i8 v[18:21], v[244:247], v[182:185], v[18:21]
	v_mfma_i32_16x16x64_i8 v[6:9], v[236:239], v[198:201], v[6:9]
	v_mfma_i32_16x16x64_i8 v[2:5], v[244:247], v[198:201], v[2:5]
	s_setprio 0
	s_barrier
	s_mov_b32 m0, s68
	s_add_u32 s0, s44, 0x44000
	s_addc_u32 s1, s45, 0
	global_load_lds_dwordx4 v148, s[0:1]
	s_mov_b32 m0, s69
	s_nop 0
	global_load_lds_dwordx4 v152, s[0:1]
	s_waitcnt vmcnt(6)
	s_barrier
	s_setprio 1
	v_mfma_i32_16x16x64_i8 v[30:33], v[202:205], v[178:181], v[30:33]
	v_mfma_i32_16x16x64_i8 v[26:29], v[210:213], v[178:181], v[26:29]
	v_mfma_i32_16x16x64_i8 v[14:17], v[202:205], v[186:189], v[14:17]
	v_mfma_i32_16x16x64_i8 v[10:13], v[210:213], v[186:189], v[10:13]
	v_mfma_i32_16x16x64_i8 v[34:37], v[202:205], v[162:165], v[78:81]
	v_mfma_i32_16x16x64_i8 v[38:41], v[210:213], v[162:165], v[74:77]
	v_mfma_i32_16x16x64_i8 v[42:45], v[202:205], v[170:173], v[62:65]
	v_mfma_i32_16x16x64_i8 v[46:49], v[210:213], v[170:173], v[58:61]
	v_mfma_i32_16x16x64_i8 v[30:33], v[206:209], v[182:185], v[30:33]
	v_mfma_i32_16x16x64_i8 v[26:29], v[214:217], v[182:185], v[26:29]
	v_mfma_i32_16x16x64_i8 v[14:17], v[206:209], v[198:201], v[14:17]
	v_mfma_i32_16x16x64_i8 v[10:13], v[214:217], v[198:201], v[10:13]
	v_mfma_i32_16x16x64_i8 v[34:37], v[206:209], v[166:169], v[34:37]
	v_mfma_i32_16x16x64_i8 v[38:41], v[214:217], v[166:169], v[38:41]
	v_mfma_i32_16x16x64_i8 v[42:45], v[206:209], v[174:177], v[42:45]
	v_mfma_i32_16x16x64_i8 v[46:49], v[214:217], v[174:177], v[46:49]
	s_setprio 0
	s_add_i32 s10, 0, 0x18000
	v_add_u32_e32 v78, s10, v191
	s_barrier
	ds_read_b128 v[58:61], v78
	ds_read_b128 v[62:65], v78 offset:1024
	ds_read_b128 v[74:77], v78 offset:2048
	ds_read_b128 v[78:81], v78 offset:3072
	s_add_u32 s0, s46, 0x44000
	s_addc_u32 s1, s47, 0
	s_mov_b32 m0, s57
	ds_read_b128 v[162:165], v194 offset:32768
	ds_read_b128 v[166:169], v194 offset:33792
	ds_read_b128 v[170:173], v194 offset:34816
	ds_read_b128 v[174:177], v194 offset:35840
	ds_read_b128 v[178:181], v194 offset:36864
	ds_read_b128 v[182:185], v194 offset:37888
	ds_read_b128 v[186:189], v194 offset:38912
	ds_read_b128 v[198:201], v194 offset:39936
	global_load_lds_dwordx4 v146, s[0:1]
	s_mov_b32 m0, s58
	s_nop 0
	global_load_lds_dwordx4 v150, s[0:1]
	s_waitcnt lgkmcnt(8)
	s_barrier
	s_waitcnt lgkmcnt(0)
	s_setprio 1
	s_waitcnt lgkmcnt(0)
	v_mfma_i32_16x16x64_i8 v[134:137], v[58:61], v[162:165], v[134:137]
	v_mfma_i32_16x16x64_i8 v[130:133], v[74:77], v[162:165], v[130:133]
	v_mfma_i32_16x16x64_i8 v[118:121], v[58:61], v[170:173], v[118:121]
	v_mfma_i32_16x16x64_i8 v[114:117], v[74:77], v[170:173], v[114:117]
	v_mfma_i32_16x16x64_i8 v[102:105], v[58:61], v[178:181], v[102:105]
	v_mfma_i32_16x16x64_i8 v[98:101], v[74:77], v[178:181], v[98:101]
	v_mfma_i32_16x16x64_i8 v[86:89], v[58:61], v[186:189], v[86:89]
	v_mfma_i32_16x16x64_i8 v[82:85], v[74:77], v[186:189], v[82:85]
	v_mfma_i32_16x16x64_i8 v[134:137], v[62:65], v[166:169], v[134:137]
	v_mfma_i32_16x16x64_i8 v[130:133], v[78:81], v[166:169], v[130:133]
	v_mfma_i32_16x16x64_i8 v[118:121], v[62:65], v[174:177], v[118:121]
	v_mfma_i32_16x16x64_i8 v[114:117], v[78:81], v[174:177], v[114:117]
	v_mfma_i32_16x16x64_i8 v[102:105], v[62:65], v[182:185], v[102:105]
	v_mfma_i32_16x16x64_i8 v[98:101], v[78:81], v[182:185], v[98:101]
	v_mfma_i32_16x16x64_i8 v[86:89], v[62:65], v[198:201], v[86:89]
	v_mfma_i32_16x16x64_i8 v[82:85], v[78:81], v[198:201], v[82:85]
	s_setprio 0
	s_barrier
; #define G_STAGE(bufoff, gbase, voff) do { _Pragma("unroll") for (int _i = 0; _i < 2; ++_i) \
;         __builtin_amdgcn_global_load_lds((const unsigned*)((const char*)(gbase) + (voff)[_i]), (LAS unsigned*)(lds + (bufoff) + ldsw + _i * 8192), 16, 0, 0); } while (0)
; #define G_WAIT_V(n) asm volatile("s_waitcnt vmcnt(" #n ")" ::: "memory")
; #define G_WAIT_L(n) asm volatile("s_waitcnt lgkmcnt(" #n ")" ::: "memory")
; #define G_BAR __builtin_amdgcn_s_barrier()
; #define G_SCHED __builtin_amdgcn_sched_barrier(0)
; template <int MODE  , class Epi, class Sched>
; __device__ __forceinline__ void gemm_phase(LAS unsigned char* lds, const GemmDesc g, const Sched& S, const Epi& E) {
;     ...
;         for (int t = 0; t < nt; t += 2) {
;             const bool last = (t == nt - 2);
;             const char* a1 = cA + (size_t)(t + 1) * kstep;
;             const char* a2 = last ? nA : cA + (size_t)(t + 2) * kstep; const char* b2 = last ? nB : cB + (size_t)(t + 2) * kstep;
;             const char* a3 = a2 + kstep; const char* b3 = b2 + kstep;
;             G_LDB(B0, 0, 0); G_SCHED; G_LDA(At, 0, 0); G_STAGE(G_SA(1, 1), a1 + hstepA, voffA);
;     ...
;             G_BAR; G_WAIT_L(0); G_MMA(0, 1, At, B1); G_BAR;
;             G_LDA(At, 1, 1); G_STAGE(G_SA(1, 0), a3, voffA);
;             G_BAR; G_WAIT_L(0); G_MMA(1, 0, At, B0); G_BAR; G_SCHED;
;             G_STAGE(G_SB(1, 1), b3 + hstepB, voffB);
;             G_WAIT_V(6); G_BAR; G_MMA(1, 1, At, B1); G_BAR;
	s_add_i32 s11, 0, 0x1c000
	s_add_i32 s0, s10, s54
	v_add_u32_e32 v154, s11, v191
	s_add_u32 s98, s44, 0x80
	s_addc_u32 s99, s45, 0
	s_mov_b32 m0, s0
	ds_read_b128 v[202:205], v154
	ds_read_b128 v[206:209], v154 offset:1024
	ds_read_b128 v[210:213], v154 offset:2048
	ds_read_b128 v[214:217], v154 offset:3072
	global_load_lds_dwordx4 v148, s[98:99]
	s_add_i32 m0, s0, 0x2000
	s_nop 0
	global_load_lds_dwordx4 v152, s[98:99]
	s_barrier
	s_waitcnt lgkmcnt(0)
	s_setprio 1
	s_waitcnt lgkmcnt(0)
	v_mfma_i32_16x16x64_i8 v[142:145], v[202:205], v[162:165], v[142:145]
	v_mfma_i32_16x16x64_i8 v[138:141], v[210:213], v[162:165], v[138:141]
	v_mfma_i32_16x16x64_i8 v[126:129], v[202:205], v[170:173], v[126:129]
	v_mfma_i32_16x16x64_i8 v[122:125], v[210:213], v[170:173], v[122:125]
	v_mfma_i32_16x16x64_i8 v[110:113], v[202:205], v[178:181], v[110:113]
	v_mfma_i32_16x16x64_i8 v[106:109], v[210:213], v[178:181], v[106:109]
	v_mfma_i32_16x16x64_i8 v[94:97], v[202:205], v[186:189], v[94:97]
	v_mfma_i32_16x16x64_i8 v[90:93], v[210:213], v[186:189], v[90:93]
	v_mfma_i32_16x16x64_i8 v[142:145], v[206:209], v[166:169], v[142:145]
	v_mfma_i32_16x16x64_i8 v[138:141], v[214:217], v[166:169], v[138:141]
	v_mfma_i32_16x16x64_i8 v[126:129], v[206:209], v[174:177], v[126:129]
	v_mfma_i32_16x16x64_i8 v[122:125], v[214:217], v[174:177], v[122:125]
	v_mfma_i32_16x16x64_i8 v[110:113], v[206:209], v[182:185], v[110:113]
	v_mfma_i32_16x16x64_i8 v[106:109], v[214:217], v[182:185], v[106:109]
	v_mfma_i32_16x16x64_i8 v[94:97], v[206:209], v[198:201], v[94:97]
	v_mfma_i32_16x16x64_i8 v[90:93], v[214:217], v[198:201], v[90:93]
	s_setprio 0
	s_mov_b32 m0, s60
	s_barrier
	ds_read_b128 v[162:165], v194 offset:49152
	ds_read_b128 v[166:169], v194 offset:50176
	ds_read_b128 v[170:173], v194 offset:51200
	ds_read_b128 v[174:177], v194 offset:52224
	ds_read_b128 v[178:181], v194 offset:53248
	ds_read_b128 v[182:185], v194 offset:54272
	ds_read_b128 v[186:189], v194 offset:55296
	ds_read_b128 v[198:201], v194 offset:56320
	s_add_u32 s98, s46, 0x80
	s_addc_u32 s99, s47, 0
	global_load_lds_dwordx4 v146, s[98:99]
	s_mov_b32 m0, s61
	s_nop 0
	global_load_lds_dwordx4 v150, s[98:99]
	s_barrier
	s_waitcnt lgkmcnt(0)
	s_setprio 1
	s_waitcnt lgkmcnt(0)
	v_mfma_i32_16x16x64_i8 v[70:73], v[58:61], v[162:165], v[70:73]
	v_mfma_i32_16x16x64_i8 v[66:69], v[74:77], v[162:165], v[66:69]
	v_mfma_i32_16x16x64_i8 v[54:57], v[58:61], v[170:173], v[54:57]
	v_mfma_i32_16x16x64_i8 v[50:53], v[74:77], v[170:173], v[50:53]
	v_mfma_i32_16x16x64_i8 v[22:25], v[58:61], v[178:181], v[22:25]
	v_mfma_i32_16x16x64_i8 v[18:21], v[74:77], v[178:181], v[18:21]
	v_mfma_i32_16x16x64_i8 v[6:9], v[58:61], v[186:189], v[6:9]
	v_mfma_i32_16x16x64_i8 v[2:5], v[74:77], v[186:189], v[2:5]
	v_mfma_i32_16x16x64_i8 v[70:73], v[62:65], v[166:169], v[70:73]
	v_mfma_i32_16x16x64_i8 v[66:69], v[78:81], v[166:169], v[66:69]
	v_mfma_i32_16x16x64_i8 v[54:57], v[62:65], v[174:177], v[54:57]
	v_mfma_i32_16x16x64_i8 v[50:53], v[78:81], v[174:177], v[50:53]
	v_mfma_i32_16x16x64_i8 v[22:25], v[62:65], v[182:185], v[22:25]
	v_mfma_i32_16x16x64_i8 v[18:21], v[78:81], v[182:185], v[18:21]
	v_mfma_i32_16x16x64_i8 v[6:9], v[62:65], v[198:201], v[6:9]
	v_mfma_i32_16x16x64_i8 v[2:5], v[78:81], v[198:201], v[2:5]
	s_setprio 0
	s_barrier
	ds_read_b128 v[232:235], v193
	ds_read_b128 v[236:239], v193 offset:1024
	ds_read_b128 v[240:243], v193 offset:2048
	ds_read_b128 v[244:247], v193 offset:3072
	s_add_u32 s0, s44, 0x44080
	s_addc_u32 s1, s45, 0
	s_add_i32 s10, s11, s54
	s_mov_b32 m0, s10
	s_nop 0
	global_load_lds_dwordx4 v148, s[0:1]
	s_add_i32 m0, s10, 0x2000
	s_nop 0
	global_load_lds_dwordx4 v152, s[0:1]
	s_waitcnt vmcnt(6)
	s_barrier
	s_setprio 1
	v_mfma_i32_16x16x64_i8 v[34:37], v[202:205], v[162:165], v[34:37]
	v_mfma_i32_16x16x64_i8 v[78:81], v[206:209], v[166:169], v[34:37]
	v_mfma_i32_16x16x64_i8 v[34:37], v[210:213], v[162:165], v[38:41]
	v_mfma_i32_16x16x64_i8 v[74:77], v[214:217], v[166:169], v[34:37]
	v_mfma_i32_16x16x64_i8 v[34:37], v[202:205], v[170:173], v[42:45]
	v_mfma_i32_16x16x64_i8 v[62:65], v[206:209], v[174:177], v[34:37]
	v_mfma_i32_16x16x64_i8 v[34:37], v[210:213], v[170:173], v[46:49]
	v_mfma_i32_16x16x64_i8 v[30:33], v[202:205], v[178:181], v[30:33]
	v_mfma_i32_16x16x64_i8 v[26:29], v[210:213], v[178:181], v[26:29]
	v_mfma_i32_16x16x64_i8 v[14:17], v[202:205], v[186:189], v[14:17]
	v_mfma_i32_16x16x64_i8 v[10:13], v[210:213], v[186:189], v[10:13]
	v_mfma_i32_16x16x64_i8 v[58:61], v[214:217], v[174:177], v[34:37]
	v_mfma_i32_16x16x64_i8 v[30:33], v[206:209], v[182:185], v[30:33]
	v_mfma_i32_16x16x64_i8 v[26:29], v[214:217], v[182:185], v[26:29]
	v_mfma_i32_16x16x64_i8 v[14:17], v[206:209], v[198:201], v[14:17]
	v_mfma_i32_16x16x64_i8 v[10:13], v[214:217], v[198:201], v[10:13]
	s_setprio 0
	s_add_i32 s77, s77, 2
	s_add_u32 s72, s72, 0x100
	s_addc_u32 s76, s76, 0
	s_cmp_gt_u32 s77, 13
	s_mov_b64 s[34:35], s[40:41]
	s_cbranch_scc1 .Lkdone_p1c
	s_barrier
	s_branch .LBB0_527

; #define G_STAGE(bufoff, gbase, voff) do { _Pragma("unroll") for (int _i = 0; _i < 2; ++_i) \
;         __builtin_amdgcn_global_load_lds((const unsigned*)((const char*)(gbase) + (voff)[_i]), (LAS unsigned*)(lds + (bufoff) + ldsw + _i * 8192), 16, 0, 0); } while (0)
; #define G_WAIT_V(n) asm volatile("s_waitcnt vmcnt(" #n ")" ::: "memory")
; #define G_BAR __builtin_amdgcn_s_barrier()
; template <int MODE  , class Epi, class Sched>
; __device__ __forceinline__ void gemm_phase(LAS unsigned char* lds, const GemmDesc g, const Sched& S, const Epi& E) {
;     ...
;     for (int i = 0; i < 2; ++i) { int R, C; stage_rc(tid * 16 + i * 8192, R, C); const int Rb = (R & ~31) + perm32(R & 31);
;         voffA[i] = (unsigned)(R * g.lda + C) * 2u; voffB[i] = (unsigned)(Rb * g.ldb + C) * 2u; }
;     const size_t kstep = (size_t)(BK * 2);
;     const size_t hstepA = (size_t)HALF * g.lda * 2, hstepB = (size_t)HALF * g.ldb * 2;
;     const size_t khb = (size_t)nt * kstep;
;     const unsigned ldsw = (unsigned)wid * 1024u;
;     const int aoff = lds_byte(wr * 64 + fr, fq * 8), boff = lds_byte(wc * 32 + fr, fq * 8);
;     ...
;     const char* cA = (const char*)(cur.type ? g.A2 : g.A) + (size_t)cur.pm * 2 * hstepA + (size_t)cur.kh * khb;
;     const char* cB = (const char*)(cur.type ? g.Bt2 : g.Bt) + (size_t)cur.pn * 2 * hstepB + (size_t)cur.kh * khb;
;     G_STAGE(G_SB(0, 0), cB, voffB); G_STAGE(G_SA(0, 0), cA, voffA); G_STAGE(G_SB(0, 1), cB + hstepB, voffB); G_STAGE(G_SA(0, 1), cA + hstepA, voffA);
;     if (wr == 1) G_BAR;
;     G_WAIT_V(4); G_BAR;
;     G_STAGE(G_SB(1, 0), cB + kstep, voffB); G_STAGE(G_SA(1, 0), cA + kstep, voffA); G_STAGE(G_SB(1, 1), cB + hstepB + kstep, voffB);
;     G_WAIT_V(6); G_BAR;
.LBB0_729:
	s_lshl_b32 s2, s2, 5
	s_mov_b64 s[12:13], 0x80
	s_and_b32 s17, s2, 0x60
	s_add_i32 m0, s62, 0x18000
	v_lshl_add_u64 v[8:9], v[8:9], 0, s[12:13]
	s_lshl_b32 s16, s1, 13
	s_lshl_b32 s2, s17, 7
	s_waitcnt vmcnt(4)
	s_barrier
	global_load_lds_dwordx4 v[8:9], off
	v_lshl_add_u64 v[6:7], v[6:7], 0, s[12:13]
	s_add_i32 m0, s62, 0x1a000
	s_add_i32 s67, s62, 0x8000
	s_add_i32 s68, s62, 0xa000
	global_load_lds_dwordx4 v[6:7], off
	v_lshl_add_u64 v[4:5], v[4:5], 0, s[12:13]
	s_mov_b32 m0, s67
	s_add_u32 s10, s46, 0x44080
	global_load_lds_dwordx4 v[4:5], off
	v_lshl_add_u64 v[2:3], v[2:3], 0, s[12:13]
	s_mov_b32 m0, s68
	s_addc_u32 s11, s47, 0
	global_load_lds_dwordx4 v[2:3], off
	s_add_i32 m0, s62, 0x1c000
	v_lshl_add_u64 v[2:3], s[10:11], 0, v[150:151]
	global_load_lds_dwordx4 v[2:3], off
	v_lshl_add_u64 v[2:3], s[10:11], 0, v[146:147]
	s_add_i32 m0, s62, 0x1e000
	s_sext_i32_i16 s76, s3
	global_load_lds_dwordx4 v[2:3], off
	v_lshrrev_b32_e32 v3, 1, v11
	v_and_b32_e32 v3, 24, v3
	v_and_b32_e32 v2, 15, v11
	v_lshlrev_b32_e32 v4, 1, v3
	v_lshl_or_b32 v1, s1, 6, v2
	v_lshl_or_b32 v2, v2, 6, v4
	v_lshlrev_b32_e32 v4, 2, v11
	v_and_b32_e32 v4, 32, v4
	v_bitop3_b32 v5, v2, s16, v4 bitop3:0xde
	v_bitop3_b32 v166, v2, s2, v4 bitop3:0xde
	v_or_b32_e32 v2, s17, v3
	v_or_b32_e32 v167, 0xfffff400, v2
	v_lshrrev_b32_e32 v3, 1, v16
	v_mul_lo_u32 v2, v15, s0
	s_movk_i32 s1, 0x4400
	v_mad_u64_u32 v[2:3], s[10:11], v3, s1, v[2:3]
	v_or_b32_e32 v2, v2, v17
	s_mov_b64 s[2:3], 0x44080
	v_add_lshl_u32 v2, v2, v18, 1
	v_mov_b32_e32 v3, v151
	v_lshl_add_u64 v[154:155], v[2:3], 0, s[2:3]
	v_lshrrev_b32_e32 v3, 1, v10
	v_mul_lo_u32 v2, v12, s0
	v_mad_u64_u32 v[2:3], s[0:1], v3, s1, v[2:3]
	s_waitcnt vmcnt(6)
	s_add_u32 s16, s48, 0x2000
	v_or_b32_e32 v2, v2, v13
	s_addc_u32 s17, s49, 0
	v_add_lshl_u32 v2, v2, v14, 1
	v_mov_b32_e32 v3, v151
	s_add_i32 s69, 0, 0x10000
	s_add_i32 s70, 0, 0x14000
	v_lshl_add_u64 v[156:157], v[2:3], 0, s[2:3]
	v_add_u32_e32 v168, s69, v166
	v_add_u32_e32 v169, 0, v5
	v_mov_b32_e32 v170, 0x7f7f7f7f
	v_add_u32_e32 v171, s70, v166
	s_mov_b32 s71, 0xc2200000
	s_mov_b64 s[18:19], 0x80000
	s_mov_b64 s[20:21], 0x90000
	s_mov_b64 s[34:35], 0xa0000
	s_mov_b64 s[40:41], 0xb0000
	v_mov_b32_e32 v172, 0x42200000
	s_waitcnt vmcnt(0)
	s_barrier

; template <int MODE  , class Epi, class Sched>
; __device__ __forceinline__ void gemm_phase(LAS unsigned char* lds, const GemmDesc g, const Sched& S, const Epi& E) {
;     ...
; #pragma unroll
;             for (int a = 0; a < 2; ++a)
; #pragma unroll
;                 for (int b = 0; b < 2; ++b)
; #pragma unroll
;                     for (int m = 0; m < 4; ++m)
; #pragma unroll
;                         for (int n = 0; n < 2; ++n) acc[a][b][m][n] = (f32x4){0.f, 0.f, 0.f, 0.f};
.LBB0_736:
	s_add_u32 s77, s46, 0x100
	v_mov_b32_e32 v18, 0
	s_addc_u32 s78, s47, 0
	s_mov_b32 s79, -2
	v_mov_b32_e32 v19, v18
	v_mov_b32_e32 v20, v18
	v_mov_b32_e32 v21, v18
	v_mov_b32_e32 v22, v18
	v_mov_b32_e32 v23, v18
	v_mov_b32_e32 v24, v18
	v_mov_b32_e32 v25, v18
	v_mov_b32_e32 v34, v18
	v_mov_b32_e32 v35, v18
	v_mov_b32_e32 v36, v18
	v_mov_b32_e32 v37, v18
	v_mov_b32_e32 v38, v18
	v_mov_b32_e32 v39, v18
	v_mov_b32_e32 v40, v18
	v_mov_b32_e32 v41, v18
	v_mov_b32_e32 v50, v18
	v_mov_b32_e32 v51, v18
	v_mov_b32_e32 v52, v18
	v_mov_b32_e32 v53, v18
	v_mov_b32_e32 v54, v18
	v_mov_b32_e32 v55, v18
	v_mov_b32_e32 v56, v18
	v_mov_b32_e32 v57, v18
	v_mov_b32_e32 v66, v18
	v_mov_b32_e32 v67, v18
	v_mov_b32_e32 v68, v18
	v_mov_b32_e32 v69, v18
	v_mov_b32_e32 v70, v18
	v_mov_b32_e32 v71, v18
	v_mov_b32_e32 v72, v18
	v_mov_b32_e32 v73, v18
	v_mov_b32_e32 v26, v18
	v_mov_b32_e32 v27, v18
	v_mov_b32_e32 v28, v18
	v_mov_b32_e32 v29, v18
	v_mov_b32_e32 v30, v18
	v_mov_b32_e32 v31, v18
	v_mov_b32_e32 v32, v18
	v_mov_b32_e32 v33, v18
	v_mov_b32_e32 v42, v18
	v_mov_b32_e32 v43, v18
	v_mov_b32_e32 v44, v18
	v_mov_b32_e32 v45, v18
	v_mov_b32_e32 v46, v18
	v_mov_b32_e32 v47, v18
	v_mov_b32_e32 v48, v18
	v_mov_b32_e32 v49, v18
	v_mov_b32_e32 v58, v18
	v_mov_b32_e32 v59, v18
	v_mov_b32_e32 v60, v18
	v_mov_b32_e32 v61, v18
	v_mov_b32_e32 v62, v18
	v_mov_b32_e32 v63, v18
	v_mov_b32_e32 v64, v18
	v_mov_b32_e32 v65, v18
	v_mov_b32_e32 v74, v18
	v_mov_b32_e32 v75, v18
	v_mov_b32_e32 v76, v18
	v_mov_b32_e32 v77, v18
	v_mov_b32_e32 v78, v18
	v_mov_b32_e32 v79, v18
	v_mov_b32_e32 v80, v18
	v_mov_b32_e32 v81, v18
	v_mov_b32_e32 v82, v18
	v_mov_b32_e32 v83, v18
	v_mov_b32_e32 v84, v18
	v_mov_b32_e32 v85, v18
	v_mov_b32_e32 v86, v18
	v_mov_b32_e32 v87, v18
	v_mov_b32_e32 v88, v18
	v_mov_b32_e32 v89, v18
	v_mov_b32_e32 v98, v18
	v_mov_b32_e32 v99, v18
	v_mov_b32_e32 v100, v18
	v_mov_b32_e32 v101, v18
	v_mov_b32_e32 v102, v18
	v_mov_b32_e32 v103, v18
	v_mov_b32_e32 v104, v18
	v_mov_b32_e32 v105, v18
	v_mov_b32_e32 v114, v18
	v_mov_b32_e32 v115, v18
	v_mov_b32_e32 v116, v18
	v_mov_b32_e32 v117, v18
	v_mov_b32_e32 v118, v18
	v_mov_b32_e32 v119, v18
	v_mov_b32_e32 v120, v18
	v_mov_b32_e32 v121, v18
	v_mov_b32_e32 v130, v18
	v_mov_b32_e32 v131, v18
	v_mov_b32_e32 v132, v18
	v_mov_b32_e32 v133, v18
	v_mov_b32_e32 v134, v18
	v_mov_b32_e32 v135, v18
	v_mov_b32_e32 v136, v18
	v_mov_b32_e32 v137, v18
	v_mov_b32_e32 v90, v18
	v_mov_b32_e32 v91, v18
	v_mov_b32_e32 v92, v18
	v_mov_b32_e32 v93, v18
	v_mov_b32_e32 v94, v18
	v_mov_b32_e32 v95, v18
	v_mov_b32_e32 v96, v18
	v_mov_b32_e32 v97, v18
	v_mov_b32_e32 v106, v18
	v_mov_b32_e32 v107, v18
	v_mov_b32_e32 v108, v18
	v_mov_b32_e32 v109, v18
	v_mov_b32_e32 v110, v18
	v_mov_b32_e32 v111, v18
	v_mov_b32_e32 v112, v18
	v_mov_b32_e32 v113, v18
	v_mov_b32_e32 v122, v18
	v_mov_b32_e32 v123, v18
	v_mov_b32_e32 v124, v18
	v_mov_b32_e32 v125, v18
	v_mov_b32_e32 v126, v18
	v_mov_b32_e32 v127, v18
	v_mov_b32_e32 v128, v18
	v_mov_b32_e32 v129, v18
	v_mov_b32_e32 v138, v18
	v_mov_b32_e32 v139, v18
	v_mov_b32_e32 v140, v18
	v_mov_b32_e32 v141, v18
	v_mov_b32_e32 v142, v18
	v_mov_b32_e32 v143, v18
	v_mov_b32_e32 v144, v18
	v_mov_b32_e32 v145, v18

; __global__ void __launch_bounds__(NTHREADS, 2) fwd_megakernel(Params p) {
	.amdhsa_kernel _Z14fwd_megakernel6Params
		.amdhsa_group_segment_fixed_size 0
		.amdhsa_private_segment_fixed_size 0
		.amdhsa_kernarg_size 384
		.amdhsa_user_sgpr_count 2
		.amdhsa_user_sgpr_dispatch_ptr 0
		.amdhsa_user_sgpr_queue_ptr 0
		.amdhsa_user_sgpr_kernarg_segment_ptr 1
		.amdhsa_user_sgpr_dispatch_id 0
		.amdhsa_user_sgpr_kernarg_preload_length 0
		.amdhsa_user_sgpr_kernarg_preload_offset 0
		.amdhsa_user_sgpr_private_segment_size 0
		.amdhsa_uses_dynamic_stack 0
		.amdhsa_enable_private_segment 0
		.amdhsa_system_sgpr_workgroup_id_x 1
		.amdhsa_system_sgpr_workgroup_id_y 0
		.amdhsa_system_sgpr_workgroup_id_z 0
		.amdhsa_system_sgpr_workgroup_info 0
		.amdhsa_system_vgpr_workitem_id 0
		.amdhsa_next_free_vgpr 248
		.amdhsa_next_free_sgpr 100
		.amdhsa_accum_offset 248
		.amdhsa_reserve_vcc 1
		.amdhsa_float_round_mode_32 0
		.amdhsa_float_round_mode_16_64 0
		.amdhsa_float_denorm_mode_32 3
		.amdhsa_float_denorm_mode_16_64 3
		.amdhsa_dx10_clamp 1
		.amdhsa_ieee_mode 1
		.amdhsa_fp16_overflow 0
		.amdhsa_tg_split 0
		.amdhsa_exception_fp_ieee_invalid_op 0
		.amdhsa_exception_fp_denorm_src 0
		.amdhsa_exception_fp_ieee_div_zero 0
		.amdhsa_exception_fp_ieee_overflow 0
		.amdhsa_exception_fp_ieee_underflow 0
		.amdhsa_exception_fp_ieee_inexact 0
		.amdhsa_exception_int_div_zero 0
	.end_amdhsa_kernel

; __global__ void __launch_bounds__(NTHREADS, 2) fwd_megakernel(Params p) {
.Lfunc_end0:
	.size	_Z14fwd_megakernel6Params, .Lfunc_end0-_Z14fwd_megakernel6Params
	.set _Z14fwd_megakernel6Params.num_vgpr, 248
	.set _Z14fwd_megakernel6Params.num_agpr, 0
	.set _Z14fwd_megakernel6Params.numbered_sgpr, 100
	.set _Z14fwd_megakernel6Params.num_named_barrier, 0
	.set _Z14fwd_megakernel6Params.private_seg_size, 0
	.set _Z14fwd_megakernel6Params.uses_vcc, 1
	.set _Z14fwd_megakernel6Params.uses_flat_scratch, 0
	.set _Z14fwd_megakernel6Params.has_dyn_sized_stack, 0
	.set _Z14fwd_megakernel6Params.has_recursion, 0
	.set _Z14fwd_megakernel6Params.has_indirect_call, 0

; __global__ void __launch_bounds__(NTHREADS, 2) fwd_megakernel(Params p) {
amdhsa.kernels:
  - .agpr_count:     0
    .args:
      - .offset:         0
        .size:           128
        .value_kind:     by_value
      - .offset:         128
        .size:           4
        .value_kind:     hidden_block_count_x
      - .offset:         132
        .size:           4
        .value_kind:     hidden_block_count_y
      - .offset:         136
        .size:           4
        .value_kind:     hidden_block_count_z
      - .offset:         140
        .size:           2
        .value_kind:     hidden_group_size_x
      - .offset:         142
        .size:           2
        .value_kind:     hidden_group_size_y
      - .offset:         144
        .size:           2
        .value_kind:     hidden_group_size_z
      - .offset:         146
        .size:           2
        .value_kind:     hidden_remainder_x
      - .offset:         148
        .size:           2
        .value_kind:     hidden_remainder_y
      - .offset:         150
        .size:           2
        .value_kind:     hidden_remainder_z
      - .offset:         168
        .size:           8
        .value_kind:     hidden_global_offset_x
      - .offset:         176
        .size:           8
        .value_kind:     hidden_global_offset_y
      - .offset:         184
        .size:           8
        .value_kind:     hidden_global_offset_z
      - .offset:         192
        .size:           2
        .value_kind:     hidden_grid_dims
      - .offset:         248
        .size:           4
        .value_kind:     hidden_dynamic_lds_size
    .group_segment_fixed_size: 0
    .kernarg_segment_align: 8
    .kernarg_segment_size: 384
    .language:       OpenCL C
    .language_version:
      - 2
      - 0
    .max_flat_workgroup_size: 512
    .name:           _Z14fwd_megakernel6Params
    .private_segment_fixed_size: 0
    .sgpr_count:     106
    .sgpr_spill_count: 8
    .symbol:         _Z14fwd_megakernel6Params.kd
    .uniform_work_group_size: 1
    .uses_dynamic_stack: false
    .vgpr_count:     248
    .vgpr_spill_count: 0
    .wavefront_size: 64
